# speedup vs baseline: 1.0056x; 1.0037x over previous
; __device__ __forceinline__ unsigned pk2(float lo, float hi) { return pg8::cvt_pk_bf16(lo, hi); }
; __device__ __forceinline__ void norm_row(const float* src, const float* g, bf16* dst, float* hdst, int lane) {
;     f32x4 v[8]; float ss = 0.f;
; #pragma unroll
;     for (int j = 0; j < 8; ++j) { v[j] = src ? *(const f32x4*)(src + 4 * lane + 256 * j) : (f32x4){0.f, 0.f, 0.f, 0.f}; ss += v[j].x * v[j].x + v[j].y * v[j].y + v[j].z * v[j].z + v[j].w * v[j].w; }
;     ss = wave_sum(ss);
;     const float rstd = rsqrtf(ss * (1.0f / DM) + EPS);
; #pragma unroll
;     for (int j = 0; j < 8; ++j) {
;         const f32x4 gg = *(const f32x4*)(g + 4 * lane + 256 * j);
;         u32x2 w; w.x = pk2(v[j].x * rstd * gg.x, v[j].y * rstd * gg.y); w.y = pk2(v[j].z * rstd * gg.z, v[j].w * rstd * gg.w);
;         *(u32x2*)(dst + 4 * lane + 256 * j) = w;
;         if (hdst) *(f32x4*)(hdst + 4 * lane + 256 * j) = v[j];
;     }
; }
.LBB0_99:
	v_lshl_add_u64 v[0:1], s[16:17], 0, v[44:45]
	v_add_co_u32_e32 v2, vcc, 0x17600000, v0
	v_lshl_add_u64 v[60:61], s[16:17], 0, v[42:43]
	s_nop 0
	v_addc_co_u32_e32 v3, vcc, 0, v1, vcc
	global_load_dwordx4 v[28:31], v[2:3], off
	global_load_dwordx4 v[24:27], v[2:3], off offset:1024
	global_load_dwordx4 v[20:23], v[2:3], off offset:2048
	global_load_dwordx4 v[16:19], v[2:3], off offset:3072
	v_add_co_u32_e32 v0, vcc, s26, v0
	s_add_i32 s40, s40, s42
	s_nop 0
	v_addc_co_u32_e32 v1, vcc, 0, v1, vcc
	global_load_dwordx4 v[12:15], v[0:1], off
	global_load_dwordx4 v[8:11], v[0:1], off offset:1024
	global_load_dwordx4 v[96:99], v[0:1], off offset:2048
	global_load_dwordx4 v[100:103], v[0:1], off offset:3072
	v_lshl_add_u64 v[42:43], v[42:43], 0, s[44:45]
	v_lshl_add_u64 v[44:45], v[44:45], 0, s[48:49]
	s_cmpk_gt_i32 s40, 0x200f
	s_waitcnt vmcnt(0)
	v_mul_f32_e32 v4, v29, v29
	v_mul_f32_e32 v5, v25, v25
	v_fmac_f32_e32 v4, v28, v28
	v_fmac_f32_e32 v5, v24, v24
	v_fmac_f32_e32 v4, v30, v30
	v_fmac_f32_e32 v5, v26, v26
	v_fmac_f32_e32 v4, v31, v31
	v_fmac_f32_e32 v5, v27, v27
	v_add_f32_e32 v4, v4, v5
	v_mul_f32_e32 v5, v21, v21
	v_fmac_f32_e32 v5, v20, v20
	v_mul_f32_e32 v2, v17, v17
	v_fmac_f32_e32 v5, v22, v22
	v_fmac_f32_e32 v2, v16, v16
	v_fmac_f32_e32 v5, v23, v23
	v_fmac_f32_e32 v2, v18, v18
	v_add_f32_e32 v4, v4, v5
	v_fmac_f32_e32 v2, v19, v19
	v_add_f32_e32 v6, v4, v2
	v_mov_b32_e32 v4, v13
	v_mov_b32_e32 v5, v9
	v_mov_b32_e32 v2, v12
	v_mov_b32_e32 v3, v8
	v_pk_mul_f32 v[4:5], v[4:5], v[4:5]
	s_nop 0
	v_pk_fma_f32 v[2:3], v[2:3], v[2:3], v[4:5]
	v_mov_b32_e32 v4, v14
	v_mov_b32_e32 v5, v10
	v_pk_fma_f32 v[2:3], v[4:5], v[4:5], v[2:3]
	v_mov_b32_e32 v4, v15
	v_mov_b32_e32 v5, v11
	v_pk_fma_f32 v[2:3], v[4:5], v[4:5], v[2:3]
	s_nop 0
	v_add_f32_e32 v2, v6, v2
	v_add_f32_e32 v56, v2, v3
	v_mov_b32_e32 v4, v96
	v_mov_b32_e32 v5, v97
	v_mov_b32_e32 v6, v98
	v_mov_b32_e32 v7, v99
	s_nop 0
	v_mov_b32_e32 v0, v100
	v_mov_b32_e32 v1, v101
	v_mov_b32_e32 v2, v102
	v_mov_b32_e32 v3, v103
	v_mov_b32_e32 v54, v5
	v_mov_b32_e32 v55, v1
	v_mov_b32_e32 v46, v4
	v_mov_b32_e32 v47, v0
	v_pk_mul_f32 v[54:55], v[54:55], v[54:55]
	s_nop 0
	v_pk_fma_f32 v[46:47], v[46:47], v[46:47], v[54:55]
	v_mov_b32_e32 v54, v6
	v_mov_b32_e32 v55, v2
	v_pk_fma_f32 v[46:47], v[54:55], v[54:55], v[46:47]
	v_mov_b32_e32 v54, v7
	v_mov_b32_e32 v55, v3
	v_pk_fma_f32 v[46:47], v[54:55], v[54:55], v[46:47]
	s_nop 0
	v_add_f32_e32 v46, v56, v46
	v_add_f32_e32 v46, v46, v47
	s_nop 1
	s_waitcnt lgkmcnt(0)
	v_add_f32_dpp v46, v46, v46 quad_perm:[1,0,3,2] row_mask:0xf bank_mask:0xf
	s_nop 1
	s_waitcnt lgkmcnt(0)
	v_add_f32_dpp v46, v46, v46 quad_perm:[2,3,0,1] row_mask:0xf bank_mask:0xf
	s_nop 1
	s_waitcnt lgkmcnt(0)
	v_add_f32_dpp v46, v46, v46 row_half_mirror row_mask:0xf bank_mask:0xf
	s_nop 1
	s_waitcnt lgkmcnt(0)
	v_add_f32_dpp v46, v46, v46 row_mirror row_mask:0xf bank_mask:0xf
	ds_bpermute_b32 v47, v52, v46
	s_waitcnt lgkmcnt(0)
	v_add_f32_e32 v46, v46, v47
	ds_bpermute_b32 v47, v53, v46
	s_waitcnt lgkmcnt(0)
	v_add_f32_e32 v46, v46, v47
	v_fmamk_f32 v46, v46, 0x3a000000, v154
	v_cmp_gt_f32_e32 vcc, s54, v46
	v_mul_f32_e32 v47, 0x4b800000, v46
	s_nop 0
	v_cndmask_b32_e32 v46, v46, v47, vcc
	v_rsq_f32_e32 v46, v46
	s_nop 0
	v_mul_f32_e32 v47, 0x45800000, v46
	v_cndmask_b32_e32 v54, v46, v47, vcc
	v_mul_f32_e32 v28, v28, v54
	v_mul_f32_e32 v29, v29, v54
	v_mul_f32_e32 v24, v24, v54
	v_mul_f32_e32 v25, v25, v54
	v_mul_f32_e32 v20, v20, v54
	v_mul_f32_e32 v21, v21, v54
	v_mul_f32_e32 v16, v16, v54
	v_mul_f32_e32 v17, v17, v54
	v_mul_f32_e32 v12, v12, v54
	v_mul_f32_e32 v13, v13, v54
	v_mul_f32_e32 v8, v8, v54
	v_mul_f32_e32 v9, v9, v54
	v_mul_f32_e32 v4, v4, v54
	v_mul_f32_e32 v5, v5, v54
	v_mul_f32_e32 v0, v0, v54
	v_mul_f32_e32 v1, v1, v54
	v_mul_f32_e32 v28, v64, v28
	v_mul_f32_e32 v29, v65, v29
	v_cvt_pk_bf16_f32 v46, v28, v29
	v_mul_f32_e32 v28, v30, v54
	v_mul_f32_e32 v28, v66, v28
	v_mul_f32_e32 v29, v31, v54
	v_mul_f32_e32 v29, v67, v29
	v_cvt_pk_bf16_f32 v47, v28, v29
	v_add_co_u32_e32 v28, vcc, s0, v60
	s_nop 1
	v_addc_co_u32_e32 v29, vcc, 0, v61, vcc
	global_store_dwordx2 v[28:29], v[46:47], off
	v_mul_f32_e32 v24, v68, v24
	v_mul_f32_e32 v25, v69, v25
	v_cvt_pk_bf16_f32 v24, v24, v25
	v_mul_f32_e32 v25, v26, v54
	v_mul_f32_e32 v25, v70, v25
	v_mul_f32_e32 v26, v27, v54
	v_mul_f32_e32 v26, v71, v26
	v_cvt_pk_bf16_f32 v25, v25, v26
	global_store_dwordx2 v[28:29], v[24:25], off offset:512
	v_mul_f32_e32 v20, v72, v20
	v_mul_f32_e32 v21, v73, v21
	v_cvt_pk_bf16_f32 v20, v20, v21
	v_mul_f32_e32 v21, v22, v54
	v_mul_f32_e32 v21, v74, v21
	v_mul_f32_e32 v22, v23, v54
	v_mul_f32_e32 v22, v75, v22
	v_cvt_pk_bf16_f32 v21, v21, v22
	global_store_dwordx2 v[28:29], v[20:21], off offset:1024
	v_mul_f32_e32 v16, v16, v76
	v_mul_f32_e32 v17, v17, v77
	v_cvt_pk_bf16_f32 v16, v16, v17
	v_mul_f32_e32 v17, v18, v54
	v_mul_f32_e32 v17, v17, v78
	v_mul_f32_e32 v18, v19, v54
	v_mul_f32_e32 v18, v18, v79
	v_cvt_pk_bf16_f32 v17, v17, v18
	global_store_dwordx2 v[28:29], v[16:17], off offset:1536
	v_mul_f32_e32 v12, v12, v80
	v_mul_f32_e32 v13, v13, v81
	v_cvt_pk_bf16_f32 v12, v12, v13
	v_mul_f32_e32 v13, v14, v54
	v_mul_f32_e32 v13, v13, v82
	v_mul_f32_e32 v14, v15, v54
	v_mul_f32_e32 v14, v14, v83
	v_cvt_pk_bf16_f32 v13, v13, v14
	global_store_dwordx2 v[28:29], v[12:13], off offset:2048
	v_mul_f32_e32 v8, v8, v84
	v_mul_f32_e32 v9, v9, v85
	v_cvt_pk_bf16_f32 v8, v8, v9
	v_mul_f32_e32 v9, v10, v54
	v_mul_f32_e32 v9, v9, v86
	v_mul_f32_e32 v10, v11, v54
	v_mul_f32_e32 v10, v10, v87
	v_cvt_pk_bf16_f32 v9, v9, v10
	global_store_dwordx2 v[28:29], v[8:9], off offset:2560
	v_mul_f32_e32 v4, v4, v88
	v_mul_f32_e32 v5, v5, v89
	v_cvt_pk_bf16_f32 v4, v4, v5
	v_mul_f32_e32 v5, v6, v54
	v_mul_f32_e32 v5, v5, v90
	v_mul_f32_e32 v6, v7, v54
	v_mul_f32_e32 v6, v6, v91
	v_cvt_pk_bf16_f32 v5, v5, v6
	global_store_dwordx2 v[28:29], v[4:5], off offset:3072
	v_mul_f32_e32 v0, v0, v92
	v_mul_f32_e32 v1, v1, v93
	v_cvt_pk_bf16_f32 v0, v0, v1
	v_mul_f32_e32 v1, v2, v54
	v_mul_f32_e32 v1, v1, v94
	v_mul_f32_e32 v2, v3, v54
	v_mul_f32_e32 v2, v2, v95
	v_cvt_pk_bf16_f32 v1, v1, v2
	global_store_dwordx2 v[28:29], v[0:1], off offset:3584
	s_cbranch_scc0 .LBB0_99

; __device__ __forceinline__ unsigned pk2(float lo, float hi) { return pg8::cvt_pk_bf16(lo, hi); }
; __device__ __forceinline__ void phase_mix(KA a, int l, LAS unsigned char* lds, int vcu, int G, int wave) {
;     ...
;     for (int t = gw; t < T_; t += NGW) {
;         const bf16* row = (const bf16*)(a->ws + WS_AO) + (size_t)t * 1024;
;         float v[16]; float ss = 0.f;
;         if (t < 8192) {
;             u32x4 x[2]; x[0] = *(const u32x4*)(row + lane * 8); x[1] = *(const u32x4*)(row + 512 + lane * 8);
; #pragma unroll
;             for (int j = 0; j < 2; ++j) { v[j * 8 + 0] = bflo(x[j].x); v[j * 8 + 1] = bfhi(x[j].x); v[j * 8 + 2] = bflo(x[j].y); v[j * 8 + 3] = bfhi(x[j].y);
;                 v[j * 8 + 4] = bflo(x[j].z); v[j * 8 + 5] = bfhi(x[j].z); v[j * 8 + 6] = bflo(x[j].w); v[j * 8 + 7] = bfhi(x[j].w); }
;         } else {
;             const float* PART = (const float*)(a->ws + WS_PART);
; #pragma unroll
;             for (int j = 0; j < 2; ++j) {
;                 const int h = j * 4 + (lane >> 4), d0 = (lane & 15) * 8, r = t - 8192;
;                 const float* pb = PART + ((size_t)(h * 33) * 16 + r) * 132;
;                 float M = -1e30f;
;                 for (int ck = 0; ck < 33; ++ck) M = fmaxf(M, pb[(size_t)ck * 16 * 132]);
;                 float L = 0.f, o[8] = {0.f, 0.f, 0.f, 0.f, 0.f, 0.f, 0.f, 0.f};
;                 for (int ck = 0; ck < 33; ++ck) { const float* p = pb + (size_t)ck * 16 * 132; const float w = __builtin_amdgcn_exp2f(p[0] - M); L += p[1] * w;
;                     const f32x4 o0 = *(const f32x4*)(p + 4 + d0), o1 = *(const f32x4*)(p + 8 + d0);
;                     o[0] += o0.x * w; o[1] += o0.y * w; o[2] += o0.z * w; o[3] += o0.w * w; o[4] += o1.x * w; o[5] += o1.y * w; o[6] += o1.z * w; o[7] += o1.w * w; }
;                 const float il = 1.0f / L;
; #pragma unroll
;                 for (int e = 0; e < 8; ++e) v[j * 8 + e] = bf2f((unsigned short)(pk2(o[e] * il, 0.f) & 0xffffu));
;             }
;         }
; #pragma unroll
;         for (int e = 0; e < 16; ++e) ss += v[e] * v[e];
;         const float rs = rsqrtf(wave_sum(ss) * (1.0f / 1024) + EPS);
; #pragma unroll
;         for (int j = 0; j < 2; ++j) { const float* g = ga + j * 512 + lane * 8; u32x4 w;
;             w.x = pk2(v[j * 8 + 0] * rs * g[0], v[j * 8 + 1] * rs * g[1]); w.y = pk2(v[j * 8 + 2] * rs * g[2], v[j * 8 + 3] * rs * g[3]);
.LBB0_133:
	v_lshlrev_b32_e32 v21, 16, v6
	v_lshlrev_b32_e32 v6, 16, v0
	v_lshlrev_b32_e32 v33, 16, v4
	v_mul_f32_e32 v4, v6, v6
	v_lshlrev_b32_e32 v19, 16, v7
	v_lshlrev_b32_e32 v7, 16, v1
	v_lshlrev_b32_e32 v23, 16, v2
	v_lshlrev_b32_e32 v25, 16, v3
	v_fmac_f32_e32 v4, v36, v36
	v_fmac_f32_e32 v4, v7, v7
	v_fmac_f32_e32 v4, v37, v37
	v_fmac_f32_e32 v4, v23, v23
	v_fmac_f32_e32 v4, v32, v32
	v_fmac_f32_e32 v4, v25, v25
	v_fmac_f32_e32 v4, v31, v31
	v_fmac_f32_e32 v4, v33, v33
	v_lshlrev_b32_e32 v34, 16, v5
	v_fmac_f32_e32 v4, v24, v24
	v_fmac_f32_e32 v4, v34, v34
	v_fmac_f32_e32 v4, v22, v22
	v_pk_mul_f32 v[0:1], v[20:21], v[20:21]
	s_lshl_b64 s[18:19], s[44:45], 12
	v_add_f32_e32 v1, v1, v4
	v_add_f32_e32 v4, v0, v1
	v_pk_mul_f32 v[0:1], v[18:19], v[18:19]
	s_add_i32 s44, s44, s7
	v_add_f32_e32 v1, v1, v4
	v_add_f32_e32 v0, v0, v1
	v_and_b32_e32 v1, 64, v196
	v_add_u32_e32 v1, 64, v1
	v_xor_b32_e32 v4, 1, v196
	v_cmp_lt_i32_e32 vcc, v4, v1
	v_add_u32_e32 v9, s7, v9
	s_cmpk_gt_i32 s44, 0x200f
	v_cndmask_b32_e32 v4, v196, v4, vcc
	v_lshlrev_b32_e32 v4, 2, v4
	s_nop 1
	v_add_u32_e32 v30, s7, v30
	s_waitcnt lgkmcnt(0)
	v_add_f32_dpp v0, v0, v0 quad_perm:[1,0,3,2] row_mask:0xf bank_mask:0xf
	v_xor_b32_e32 v4, 2, v196
	v_cmp_lt_i32_e32 vcc, v4, v1
	s_nop 1
	v_cndmask_b32_e32 v4, v196, v4, vcc
	v_lshlrev_b32_e32 v4, 2, v4
	s_nop 1
	s_waitcnt lgkmcnt(0)
	v_add_f32_dpp v0, v0, v0 quad_perm:[2,3,0,1] row_mask:0xf bank_mask:0xf
	v_xor_b32_e32 v4, 4, v196
	v_cmp_lt_i32_e32 vcc, v4, v1
	s_nop 1
	v_cndmask_b32_e32 v4, v196, v4, vcc
	v_lshlrev_b32_e32 v4, 2, v4
	s_nop 1
	s_waitcnt lgkmcnt(0)
	v_add_f32_dpp v0, v0, v0 row_half_mirror row_mask:0xf bank_mask:0xf
	v_xor_b32_e32 v4, 8, v196
	v_cmp_lt_i32_e32 vcc, v4, v1
	s_nop 1
	v_cndmask_b32_e32 v4, v196, v4, vcc
	v_lshlrev_b32_e32 v4, 2, v4
	s_nop 1
	s_waitcnt lgkmcnt(0)
	v_add_f32_dpp v0, v0, v0 row_mirror row_mask:0xf bank_mask:0xf
	v_xor_b32_e32 v4, 16, v196
	v_cmp_lt_i32_e32 vcc, v4, v1
	s_nop 1
	v_cndmask_b32_e32 v4, v196, v4, vcc
	v_lshlrev_b32_e32 v4, 2, v4
	ds_bpermute_b32 v4, v4, v0
	s_waitcnt lgkmcnt(0)
	v_add_f32_e32 v0, v0, v4
	v_xor_b32_e32 v4, 32, v196
	v_cmp_lt_i32_e32 vcc, v4, v1
	s_nop 1
	v_cndmask_b32_e32 v1, v196, v4, vcc
	v_lshlrev_b32_e32 v1, 2, v1
	ds_bpermute_b32 v1, v1, v0
	s_waitcnt lgkmcnt(0)
	v_add_f32_e32 v0, v0, v1
	v_fmamk_f32 v0, v0, 0x3a800000, v154
	v_mul_f32_e32 v1, 0x4b800000, v0
	v_cmp_gt_f32_e32 vcc, s54, v0
	s_nop 1
	v_cndmask_b32_e32 v0, v0, v1, vcc
	v_rsq_f32_e32 v0, v0
	s_nop 0
	v_mul_f32_e32 v1, 0x45800000, v0
	v_cndmask_b32_e32 v35, v0, v1, vcc
	v_mul_f32_e32 v0, v35, v6
	v_mul_f32_e32 v1, v35, v36
	v_mul_f32_e32 v0, v232, v0
	v_mul_f32_e32 v1, v233, v1
	v_cvt_pk_bf16_f32 v0, v0, v1
	v_mul_f32_e32 v1, v35, v7
	v_mul_f32_e32 v4, v35, v37
	v_mul_f32_e32 v5, v35, v32
	v_lshl_add_u64 v[6:7], v[12:13], 0, s[18:19]
	v_mul_f32_e32 v18, v35, v18
	v_mul_f32_e32 v1, v234, v1
	v_mul_f32_e32 v2, v235, v4
	v_cvt_pk_bf16_f32 v1, v1, v2
	v_mul_f32_e32 v4, v35, v23
	v_mul_f32_e32 v23, v35, v31
	v_mul_f32_e32 v2, v236, v4
	v_mul_f32_e32 v3, v237, v5
	v_cvt_pk_bf16_f32 v2, v2, v3
	v_mul_f32_e32 v3, v35, v25
	v_mul_f32_e32 v3, v238, v3
	v_mul_f32_e32 v4, v239, v23
	v_cvt_pk_bf16_f32 v3, v3, v4
	global_store_dwordx4 v[6:7], v[0:3], off
	s_nop 1
	v_mul_f32_e32 v4, v35, v22
	v_mul_f32_e32 v2, v35, v33
	v_mul_f32_e32 v3, v35, v24
	v_mul_f32_e32 v5, v35, v20
	v_mul_f32_e32 v0, v240, v2
	v_mul_f32_e32 v1, v241, v3
	v_cvt_pk_bf16_f32 v0, v0, v1
	v_mul_f32_e32 v1, v35, v34
	v_mul_f32_e32 v1, v242, v1
	v_mul_f32_e32 v2, v243, v4
	v_cvt_pk_bf16_f32 v1, v1, v2
	v_mul_f32_e32 v4, v35, v21
	v_mul_f32_e32 v2, v4, v244
	v_mul_f32_e32 v3, v5, v245
	v_cvt_pk_bf16_f32 v2, v2, v3
	v_mul_f32_e32 v3, v35, v19
	v_mul_f32_e32 v3, v3, v246
	v_mul_f32_e32 v4, v18, v247
	v_cvt_pk_bf16_f32 v3, v3, v4
	global_store_dwordx4 v[6:7], v[0:3], off offset:1024
	s_nop 1
	s_cbranch_scc1 .LBB0_142

; __device__ __forceinline__ u32x4_h zero4u() { unsigned z = 0u; asm volatile("" : "+v"(z)); return (u32x4_h){z, z, z, z}; }
; #define LAS __attribute__((address_space(3)))
; __device__ __forceinline__ void phase_mix(KA a, int l, LAS unsigned char* lds, int vcu, int G, int wave) {
;     ...
;     constexpr int RS = 1032;
;     LAS bf16* tile = (LAS bf16*)lds;
;     const bf16* YT = (const bf16*)(a->ws + WS_YT);
;     for (int tl = vcu; tl < (T_ + 31) / 32; tl += G) {
;         const int t0 = tl * 32;
;         __syncthreads();
; #pragma unroll 2
;         for (int p = 0; p < 8; ++p) {
;             const int c = p * 128 + (tid >> 2), tk = (tid & 3) * 8;
;             u32x4 x = zero4u();
;             if (t0 + tk < T_) x = *(const u32x4*)(YT + (size_t)c * TP + t0 + tk);
;             tile[(tk + 0) * RS + c] = (bf16)(x.x & 0xffffu); tile[(tk + 1) * RS + c] = (bf16)(x.x >> 16);
;             tile[(tk + 2) * RS + c] = (bf16)(x.y & 0xffffu); tile[(tk + 3) * RS + c] = (bf16)(x.y >> 16);
;             tile[(tk + 4) * RS + c] = (bf16)(x.z & 0xffffu); tile[(tk + 5) * RS + c] = (bf16)(x.z >> 16);
;             tile[(tk + 6) * RS + c] = (bf16)(x.w & 0xffffu); tile[(tk + 7) * RS + c] = (bf16)(x.w >> 16);
;         }
.LBB0_142:
	s_cmpk_gt_i32 s11, 0x100
	s_cbranch_scc1 .LBB0_158
	s_xor_b32 s11, s11, 0x80
	v_readlane_b32 s0, v253, 25
	s_lshl_b64 s[18:19], s[42:43], 2
	s_waitcnt lgkmcnt(0)
	s_add_u32 s18, s48, s18
	v_or_b32_e32 v0, s0, v27
	s_addc_u32 s19, s49, s19
	v_ashrrev_i32_e32 v2, 2, v0
	v_lshlrev_b32_e32 v0, 3, v26
	v_mov_b32_e32 v9, v149
	s_movk_i32 s0, 0x4200
	v_and_b32_e32 v16, 24, v0
	v_lshl_add_u64 v[4:5], s[18:19], 0, v[148:149]
	v_lshl_add_u64 v[6:7], s[40:41], 0, v[8:9]
	v_mad_i64_i32 v[0:1], s[18:19], v2, s0, 0
	v_and_b32_e32 v9, 3, v26
	v_lshl_or_b32 v0, v9, 4, v0
	v_lshl_add_u64 v[0:1], s[16:17], 0, v[0:1]
	s_mov_b64 s[18:19], 0x1fe20000
	s_lshl_b32 s42, s11, 5
	v_readlane_b32 s0, v253, 11
	v_mul_u32_u24_e32 v3, 0x810, v16
	v_lshl_add_u64 v[10:11], v[0:1], 0, s[18:19]
	v_lshlrev_b32_e32 v0, 1, v2
	s_add_i32 s7, s0, s42
	v_readlane_b32 s0, v254, 42
	s_lshl_b32 s5, s15, 5
	v_add3_u32 v17, v3, v0, 0
	v_lshlrev_b32_e32 v75, 5, v9
	v_add_u32_e32 v76, 0x700, v0
	v_add_u32_e32 v17, v17, v75
	v_add_u32_e32 v76, v76, v75
	s_lshr_b32 s1, s81, 1
	v_and_b32_e32 v76, 0x7ff, v76
	s_lshl_b32 s1, s1, 5
	v_add_u32_e32 v76, v76, v3
	v_add_u32_e32 v77, s1, v8
	v_add_u32_e32 v74, 0x400, v77
	v_and_b32_e32 v77, 0x7ff, v77
	v_and_b32_e32 v74, 0x7ff, v74
	v_add_u32_e32 v18, s0, v77
	v_add_u32_e32 v74, s0, v74
	s_mov_b32 s9, s11
	v_readlane_b32 s1, v253, 26
	global_load_dwordx2 v[232:233], v[4:5], off
	global_load_dwordx2 v[234:235], v[4:5], off offset:8
	global_load_dwordx2 v[236:237], v[4:5], off offset:16
	global_load_dwordx2 v[238:239], v[4:5], off offset:24
	global_load_dwordx2 v[240:241], v[4:5], off offset:2048
	global_load_dwordx2 v[242:243], v[4:5], off offset:2056
	global_load_dwordx2 v[244:245], v[4:5], off offset:2064
	global_load_dwordx2 v[246:247], v[4:5], off offset:2072
	s_branch .LBB0_145

; __device__ __forceinline__ u32x4_h zero4u() { unsigned z = 0u; asm volatile("" : "+v"(z)); return (u32x4_h){z, z, z, z}; }
; __device__ __forceinline__ void phase_mix(KA a, int l, LAS unsigned char* lds, int vcu, int G, int wave) {
;     ...
;         for (int p = 0; p < 8; ++p) {
;             const int c = p * 128 + (tid >> 2), tk = (tid & 3) * 8;
;             u32x4 x = zero4u();
;             if (t0 + tk < T_) x = *(const u32x4*)(YT + (size_t)c * TP + t0 + tk);
;             tile[(tk + 0) * RS + c] = (bf16)(x.x & 0xffffu); tile[(tk + 1) * RS + c] = (bf16)(x.x >> 16);
;             tile[(tk + 2) * RS + c] = (bf16)(x.y & 0xffffu); tile[(tk + 3) * RS + c] = (bf16)(x.y >> 16);
;             tile[(tk + 4) * RS + c] = (bf16)(x.z & 0xffffu); tile[(tk + 5) * RS + c] = (bf16)(x.z >> 16);
;             tile[(tk + 6) * RS + c] = (bf16)(x.w & 0xffffu); tile[(tk + 7) * RS + c] = (bf16)(x.w >> 16);
;         }
.Lmix_tile_noload:
	s_or_b64 exec, exec, s[22:23]
	s_waitcnt vmcnt(0)
	ds_write_b16 v17, v40 offset:0
	ds_write_b16_d16_hi v17, v40 offset:2064
	ds_write_b16 v17, v41 offset:4128
	ds_write_b16_d16_hi v17, v41 offset:6192
	ds_write_b16 v17, v42 offset:8256
	ds_write_b16_d16_hi v17, v42 offset:10320
	ds_write_b16 v17, v43 offset:12384
	ds_write_b16_d16_hi v17, v43 offset:14448
	ds_write_b16 v17, v44 offset:256
	ds_write_b16_d16_hi v17, v44 offset:2320
	ds_write_b16 v17, v45 offset:4384
	ds_write_b16_d16_hi v17, v45 offset:6448
	ds_write_b16 v17, v46 offset:8512
	ds_write_b16_d16_hi v17, v46 offset:10576
	ds_write_b16 v17, v47 offset:12640
	ds_write_b16_d16_hi v17, v47 offset:14704
	ds_write_b16 v17, v48 offset:512
	ds_write_b16_d16_hi v17, v48 offset:2576
	ds_write_b16 v17, v49 offset:4640
	ds_write_b16_d16_hi v17, v49 offset:6704
	ds_write_b16 v17, v50 offset:8768
	ds_write_b16_d16_hi v17, v50 offset:10832
	ds_write_b16 v17, v51 offset:12896
	ds_write_b16_d16_hi v17, v51 offset:14960
	ds_write_b16 v17, v52 offset:768
	ds_write_b16_d16_hi v17, v52 offset:2832
	ds_write_b16 v17, v53 offset:4896
	ds_write_b16_d16_hi v17, v53 offset:6960
	ds_write_b16 v17, v54 offset:9024
	ds_write_b16_d16_hi v17, v54 offset:11088
	ds_write_b16 v17, v55 offset:13152
	ds_write_b16_d16_hi v17, v55 offset:15216
	ds_write_b16 v17, v56 offset:1024
	ds_write_b16_d16_hi v17, v56 offset:3088
	ds_write_b16 v17, v57 offset:5152
	ds_write_b16_d16_hi v17, v57 offset:7216
	ds_write_b16 v17, v58 offset:9280
	ds_write_b16_d16_hi v17, v58 offset:11344
	ds_write_b16 v17, v59 offset:13408
	ds_write_b16_d16_hi v17, v59 offset:15472
	ds_write_b16 v17, v60 offset:1280
	ds_write_b16_d16_hi v17, v60 offset:3344
	ds_write_b16 v17, v61 offset:5408
	ds_write_b16_d16_hi v17, v61 offset:7472
	ds_write_b16 v17, v62 offset:9536
	ds_write_b16_d16_hi v17, v62 offset:11600
	ds_write_b16 v17, v63 offset:13664
	ds_write_b16_d16_hi v17, v63 offset:15728
	ds_write_b16 v17, v64 offset:1536
	ds_write_b16_d16_hi v17, v64 offset:3600
	ds_write_b16 v17, v65 offset:5664
	ds_write_b16_d16_hi v17, v65 offset:7728
	ds_write_b16 v17, v66 offset:9792
	ds_write_b16_d16_hi v17, v66 offset:11856
	ds_write_b16 v17, v67 offset:13920
	ds_write_b16_d16_hi v17, v67 offset:15984
	ds_write_b16 v76, v68 offset:0
	ds_write_b16_d16_hi v76, v68 offset:2064
	ds_write_b16 v76, v69 offset:4128
	ds_write_b16_d16_hi v76, v69 offset:6192
	ds_write_b16 v76, v70 offset:8256
	ds_write_b16_d16_hi v76, v70 offset:10320
	ds_write_b16 v76, v71 offset:12384
	ds_write_b16_d16_hi v76, v71 offset:14448

; #define LAS __attribute__((address_space(3)))
; __device__ __forceinline__ unsigned pk2(float lo, float hi) { return pg8::cvt_pk_bf16(lo, hi); }
; __device__ __forceinline__ float bflo(unsigned w) { return __uint_as_float(w << 16); }
; __device__ __forceinline__ float bfhi(unsigned w) { return __uint_as_float(w & 0xffff0000u); }
; __device__ __forceinline__ void phase_mix(KA a, int l, LAS unsigned char* lds, int vcu, int G, int wave) {
;     ...
; #pragma unroll 1
;         for (int r = 0; r < 4; ++r) {
;             const int tr = wave * 4 + r, t = t0 + tr;
;             u32x4 x[2]; x[0] = *(const LAS u32x4*)(tile + tr * RS + lane * 8); x[1] = *(const LAS u32x4*)(tile + tr * RS + 512 + lane * 8);
;             float v[16]; float ss = 0.f;
; #pragma unroll
;             for (int j = 0; j < 2; ++j) { v[j * 8 + 0] = bflo(x[j].x); v[j * 8 + 1] = bfhi(x[j].x); v[j * 8 + 2] = bflo(x[j].y); v[j * 8 + 3] = bfhi(x[j].y);
;                 v[j * 8 + 4] = bflo(x[j].z); v[j * 8 + 5] = bfhi(x[j].z); v[j * 8 + 6] = bflo(x[j].w); v[j * 8 + 7] = bfhi(x[j].w); }
; #pragma unroll
;             for (int e = 0; e < 16; ++e) ss += v[e] * v[e];
;             const float rs = rsqrtf(wave_sum(ss) * (1.0f / 1024) + EPS);
; #pragma unroll
;             for (int j = 0; j < 2; ++j) { const float* g = gy + j * 512 + lane * 8; u32x4 w;
;                 w.x = pk2(v[j * 8 + 0] * rs * g[0], v[j * 8 + 1] * rs * g[1]); w.y = pk2(v[j * 8 + 2] * rs * g[2], v[j * 8 + 3] * rs * g[3]);
;                 w.z = pk2(v[j * 8 + 4] * rs * g[4], v[j * 8 + 5] * rs * g[5]); w.w = pk2(v[j * 8 + 6] * rs * g[6], v[j * 8 + 7] * rs * g[7]);
;                 if (t < T_) *(u32x4*)(MIX + (size_t)t * 2048 + 1024 + j * 512 + lane * 8) = w; }
.LBB0_153:
	v_add_u32_e32 v8, s11, v18
	ds_read_b128 v[0:3], v8
	v_add_u32_e32 v8, s11, v74
	ds_read_b128 v[12:15], v8
	s_cmpk_lt_i32 s40, 0x2010
	s_cselect_b64 s[22:23], -1, 0
	s_ashr_i32 s41, s40, 31
	s_waitcnt lgkmcnt(1)
	v_and_b32_e32 v33, 0xffff0000, v0
	v_lshlrev_b32_e32 v32, 16, v0
	v_lshlrev_b32_e32 v36, 16, v2
	v_and_b32_e32 v37, 0xffff0000, v2
	v_mul_f32_e32 v2, v33, v33
	v_lshlrev_b32_e32 v34, 16, v1
	v_fmac_f32_e32 v2, v32, v32
	v_and_b32_e32 v35, 0xffff0000, v1
	v_fmac_f32_e32 v2, v34, v34
	v_fmac_f32_e32 v2, v35, v35
	v_fmac_f32_e32 v2, v36, v36
	v_lshlrev_b32_e32 v38, 16, v3
	v_fmac_f32_e32 v2, v37, v37
	v_and_b32_e32 v39, 0xffff0000, v3
	v_fmac_f32_e32 v2, v38, v38
	s_waitcnt lgkmcnt(0)
	v_lshlrev_b32_e32 v28, 16, v12
	v_fmac_f32_e32 v2, v39, v39
	v_and_b32_e32 v27, 0xffff0000, v12
	v_fmac_f32_e32 v2, v28, v28
	v_lshlrev_b32_e32 v26, 16, v13
	v_fmac_f32_e32 v2, v27, v27
	v_and_b32_e32 v25, 0xffff0000, v13
	v_fmac_f32_e32 v2, v26, v26
	v_and_b32_e32 v12, 0xffff0000, v14
	v_lshlrev_b32_e32 v13, 16, v14
	v_fmac_f32_e32 v2, v25, v25
	v_pk_mul_f32 v[0:1], v[12:13], v[12:13]
	v_and_b32_e32 v8, 0xffff0000, v15
	v_add_f32_e32 v1, v1, v2
	v_lshlrev_b32_e32 v9, 16, v15
	v_add_f32_e32 v2, v0, v1
	v_pk_mul_f32 v[0:1], v[8:9], v[8:9]
	s_lshl_b64 s[18:19], s[40:41], 12
	v_add_f32_e32 v1, v1, v2
	v_add_f32_e32 v0, v0, v1
	s_nop 1
	s_cmpk_gt_i32 s40, 0x200f
	s_waitcnt lgkmcnt(0)
	v_add_f32_dpp v0, v0, v0 quad_perm:[1,0,3,2] row_mask:0xf bank_mask:0xf
	s_nop 1
	s_waitcnt lgkmcnt(0)
	v_add_f32_dpp v0, v0, v0 quad_perm:[2,3,0,1] row_mask:0xf bank_mask:0xf
	s_nop 1
	s_waitcnt lgkmcnt(0)
	v_add_f32_dpp v0, v0, v0 row_half_mirror row_mask:0xf bank_mask:0xf
	s_nop 1
	s_waitcnt lgkmcnt(0)
	v_add_f32_dpp v0, v0, v0 row_mirror row_mask:0xf bank_mask:0xf
	ds_bpermute_b32 v1, v23, v0
	s_waitcnt lgkmcnt(0)
	v_add_f32_e32 v0, v0, v1
	ds_bpermute_b32 v1, v24, v0
	s_waitcnt lgkmcnt(0)
	v_add_f32_e32 v0, v0, v1
	v_fmamk_f32 v0, v0, 0x3a800000, v154
	v_mul_f32_e32 v1, 0x4b800000, v0
	v_cmp_gt_f32_e32 vcc, s54, v0
	s_nop 1
	v_cndmask_b32_e32 v0, v0, v1, vcc
	v_rsq_f32_e32 v0, v0
	s_nop 0
	v_mul_f32_e32 v1, 0x45800000, v0
	v_cndmask_b32_e32 v29, v0, v1, vcc
	v_mul_f32_e32 v0, v29, v32
	v_mul_f32_e32 v1, v29, v33
	v_mul_f32_e32 v0, v232, v0
	v_mul_f32_e32 v1, v233, v1
	v_cvt_pk_bf16_f32 v0, v0, v1
	v_mul_f32_e32 v1, v29, v34
	v_mul_f32_e32 v14, v29, v35
	v_mul_f32_e32 v15, v29, v37
	v_mul_f32_e32 v32, v29, v39
	v_mul_f32_e32 v1, v234, v1
	v_mul_f32_e32 v2, v235, v14
	v_cvt_pk_bf16_f32 v1, v1, v2
	v_mul_f32_e32 v14, v29, v36
	v_mul_f32_e32 v2, v236, v14
	v_mul_f32_e32 v3, v237, v15
	v_cvt_pk_bf16_f32 v2, v2, v3
	v_mul_f32_e32 v3, v29, v38
	v_lshl_add_u64 v[14:15], v[6:7], 0, s[18:19]
	v_mul_f32_e32 v3, v238, v3
	v_mul_f32_e32 v30, v239, v32
	v_cvt_pk_bf16_f32 v3, v3, v30
	s_cbranch_scc1 .LBB0_155
	global_store_dwordx4 v[14:15], v[0:3], off offset:2048
	s_nop 1

; __device__ __forceinline__ void phase_prep(KA a, int l, int vcu, int G, int wave) {
;     ...
;     for (int t = gw; t < T_; t += NGW) {
;         const bf16* qrow = (const bf16*)(a->ws + WS_QRAW) + (size_t)t * 1536 + hh * QKD + 8 * j;
;         const bf16* kvrow = (const bf16*)(a->ws + WS_KVRAW) + (size_t)t * 2048 + hh * 256 + 8 * j;
;         const bf16* krow = (const bf16*)(a->ws + WS_ATT) + (size_t)t * 1024 + 768 + 8 * j;
;         const f32x4* cst = (const f32x4*)((const f32x2*)(a->ws + WS_ROPE) + t * 32 + 8 * (j & 3));
;         const u32x4 q0 = *(const u32x4*)qrow, q1 = *(const u32x4*)(qrow + 64), q2 = *(const u32x4*)(qrow + 128);
;         const u32x4 k0 = *(const u32x4*)kvrow, k1 = *(const u32x4*)(kvrow + 64), k2 = *(const u32x4*)krow;
;         const f32x4 cs0 = cst[0], cs1 = cst[1], cs2 = cst[2], cs3 = cst[3];
;         const float cc[8] = {cs0.x, cs0.z, cs1.x, cs1.z, cs2.x, cs2.z, cs3.x, cs3.z}, sn[8] = {cs0.y, cs0.w, cs1.y, cs1.w, cs2.y, cs2.w, cs3.y, cs3.w};
; #pragma unroll
;         for (int which = 0; which < 2; ++which) {
;             float v[24];
;             unpack8(which ? k0 : q0, v); unpack8(which ? k1 : q1, v + 8); unpack8(which ? k2 : q2, v + 16);
;             float ss = 0.f;
; #pragma unroll
;             for (int e = 0; e < 24; ++e) ss += v[e] * v[e];
;             ss += __shfl_xor(ss, 1); ss += __shfl_xor(ss, 2); ss += __shfl_xor(ss, 4);
;             const float rs = rsqrtf(ss * (1.0f / QKD) + EPS) * (which ? 1.0f : 1.0f);
; #pragma unroll
;             for (int e = 0; e < 24; ++e) v[e] *= rs * (which ? gkv[e] : gqv[e]);
;             float o2[8];
; #pragma unroll
;             for (int e = 0; e < 8; ++e) { const float p = __shfl_xor(v[16 + e], 4); o2[e] = v[16 + e] * cc[e] + (j < 4 ? -p : p) * sn[e]; }
;             bf16* d = (bf16*)(a->ws + (which ? WS_K : WS_Q)) + ((size_t)hh * TP + t) * QKD + 8 * j;
;             *(u32x4*)d = pack8(v); *(u32x4*)(d + 64) = pack8(v + 8); *(u32x4*)(d + 128) = pack8(o2);
.LBB0_375:
	s_nop 0
	v_lshl_add_u64 v[48:49], v[78:79], 0, v[148:149]
	global_load_dwordx4 v[90:93], v[48:49], off offset:-128
	global_load_dwordx4 v[94:97], v[48:49], off
	global_load_dwordx4 v[98:101], v[48:49], off offset:128
	v_lshl_add_u64 v[50:51], v[80:81], 0, v[148:149]
	s_mov_b32 s3, 0x25f10000
	s_ashr_i32 s47, s46, 31
	v_add_co_u32_e32 v48, vcc, s3, v50
	v_lshl_add_u64 v[52:53], s[56:57], 0, v[148:149]
	v_lshl_add_u64 v[60:61], s[46:47], 3, v[76:77]
	v_addc_co_u32_e32 v49, vcc, 0, v51, vcc
	global_load_dwordx4 v[72:75], v[48:49], off
	global_load_dwordx4 v[68:71], v[48:49], off offset:128
	global_load_dwordx4 v[64:67], v[52:53], off
	s_nop 0
	global_load_dwordx4 v[48:51], v[60:61], off offset:48
	global_load_dwordx4 v[52:55], v[60:61], off offset:32
	global_load_dwordx4 v[56:59], v[60:61], off offset:16
	s_nop 0
	global_load_dwordx4 v[60:63], v[60:61], off
	s_mov_b32 s3, 0x28010000
	s_add_i32 s44, s44, s42
	s_add_i32 s46, s46, s7
	s_add_u32 s56, s56, s58
	s_addc_u32 s57, s57, s59
	v_lshl_add_u64 v[78:79], v[78:79], 0, s[48:49]
	v_lshl_add_u64 v[80:81], v[80:81], 0, s[52:53]
	s_cmpk_gt_i32 s44, 0x200f
	s_waitcnt vmcnt(0)
	v_and_b32_e32 v102, 0xffff0000, v90
	v_lshlrev_b32_e32 v89, 16, v90
	v_lshlrev_b32_e32 v112, 16, v93
	v_and_b32_e32 v113, 0xffff0000, v93
	v_mul_f32_e32 v93, v102, v102
	v_lshlrev_b32_e32 v103, 16, v91
	v_fmac_f32_e32 v93, v89, v89
	v_and_b32_e32 v104, 0xffff0000, v91
	v_fmac_f32_e32 v93, v103, v103
	v_lshlrev_b32_e32 v105, 16, v92
	v_fmac_f32_e32 v93, v104, v104
	v_and_b32_e32 v92, 0xffff0000, v92
	v_fmac_f32_e32 v93, v105, v105
	v_fmac_f32_e32 v93, v92, v92
	v_fmac_f32_e32 v93, v112, v112
	v_lshlrev_b32_e32 v114, 16, v94
	v_fmac_f32_e32 v93, v113, v113
	v_and_b32_e32 v115, 0xffff0000, v94
	v_fmac_f32_e32 v93, v114, v114
	v_lshlrev_b32_e32 v116, 16, v95
	v_fmac_f32_e32 v93, v115, v115
	v_and_b32_e32 v117, 0xffff0000, v95
	v_fmac_f32_e32 v93, v116, v116
	v_lshlrev_b32_e32 v118, 16, v96
	v_fmac_f32_e32 v93, v117, v117
	v_and_b32_e32 v119, 0xffff0000, v96
	v_fmac_f32_e32 v93, v118, v118
	v_lshlrev_b32_e32 v120, 16, v97
	v_fmac_f32_e32 v93, v119, v119
	v_and_b32_e32 v121, 0xffff0000, v97
	v_fmac_f32_e32 v93, v120, v120
	v_and_b32_e32 v84, 0xffff0000, v98
	v_lshlrev_b32_e32 v85, 16, v98
	v_fmac_f32_e32 v93, v121, v121
	v_pk_mul_f32 v[90:91], v[84:85], v[84:85]
	v_and_b32_e32 v106, 0xffff0000, v99
	v_add_f32_e32 v91, v91, v93
	v_lshlrev_b32_e32 v107, 16, v99
	v_add_f32_e32 v93, v90, v91
	v_pk_mul_f32 v[90:91], v[106:107], v[106:107]
	v_and_b32_e32 v108, 0xffff0000, v100
	v_add_f32_e32 v91, v91, v93
	v_lshlrev_b32_e32 v109, 16, v100
	v_add_f32_e32 v93, v90, v91
	v_pk_mul_f32 v[90:91], v[108:109], v[108:109]
	v_and_b32_e32 v110, 0xffff0000, v101
	v_add_f32_e32 v91, v91, v93
	v_lshlrev_b32_e32 v111, 16, v101
	v_add_f32_e32 v93, v90, v91
	v_pk_mul_f32 v[90:91], v[110:111], v[110:111]
	s_nop 0
	v_add_f32_e32 v91, v91, v93
	v_add_f32_e32 v90, v90, v91
	s_nop 1
	v_add_f32_dpp v90, v90, v90 quad_perm:[1,0,3,2] row_mask:0xf bank_mask:0xf
	s_nop 1
	v_add_f32_dpp v90, v90, v90 quad_perm:[2,3,0,1] row_mask:0xf bank_mask:0xf
	s_nop 1
	v_add_f32_dpp v90, v90, v90 row_half_mirror row_mask:0xf bank_mask:0xf
	v_fmamk_f32 v90, v90, 0x3baaaaab, v154
	v_cmp_gt_f32_e32 vcc, s9, v90
	v_mul_f32_e32 v91, 0x4b800000, v90
	s_nop 0
	v_cndmask_b32_e32 v90, v90, v91, vcc
	v_rsq_f32_e32 v90, v90
	s_nop 0
	v_mul_f32_e32 v91, 0x45800000, v90
	v_cndmask_b32_e32 v123, v90, v91, vcc
	v_mul_f32_e32 v94, v4, v123
	v_mul_f32_e32 v95, v5, v123
	v_mul_f32_e32 v94, v94, v105
	v_mul_f32_e32 v97, v95, v92
	v_mul_f32_e32 v92, v6, v123
	v_mul_f32_e32 v105, v40, v123
	v_mul_f32_e32 v98, v92, v112
	v_mul_f32_e32 v92, v7, v123
	v_mul_f32_e32 v112, v105, v85
	v_mul_f32_e32 v85, v41, v123
	v_mul_f32_e32 v101, v92, v113
	v_mul_f32_e32 v92, v16, v123
	v_mul_f32_e32 v84, v85, v84
	v_mul_f32_e32 v85, v42, v123
	v_mul_f32_e32 v92, v92, v114
	v_mul_f32_e32 v96, v18, v123
	v_mul_f32_e32 v114, v85, v107
	v_mul_f32_e32 v85, v43, v123
	v_mul_f32_e32 v91, v2, v123
	v_mul_f32_e32 v96, v96, v116
	v_mul_f32_e32 v100, v20, v123
	v_mul_f32_e32 v116, v85, v106
	v_mul_f32_e32 v85, v44, v123
	v_mul_f32_e32 v91, v91, v103
	v_mul_f32_e32 v100, v100, v118
	v_mul_f32_e32 v103, v22, v123
	v_mul_f32_e32 v118, v85, v109
	v_mul_f32_e32 v85, v45, v123
	v_mul_f32_e32 v103, v103, v120
	v_mul_f32_e32 v120, v85, v108
	v_mul_f32_e32 v85, v46, v123
	v_mul_f32_e32 v122, v85, v111
	v_mul_f32_e32 v85, v47, v123
	v_mul_f32_e32 v124, v85, v110
	s_nop 1
	v_mov_b32_dpp v85, v112 quad_perm:[3,2,1,0] row_mask:0xf bank_mask:0xf
	s_nop 1
	v_mov_b32_dpp v85, v85 row_half_mirror row_mask:0xf bank_mask:0xf
	v_mul_f32_e32 v95, v17, v123
	v_mul_f32_e32 v95, v95, v115
	v_mul_f32_e32 v99, v19, v123
	v_mul_f32_e32 v99, v99, v117
	s_waitcnt lgkmcnt(0)
	v_cndmask_b32_e64 v113, v85, -v85, s[40:41]
	s_nop 1
	v_mov_b32_dpp v85, v84 quad_perm:[3,2,1,0] row_mask:0xf bank_mask:0xf
	s_nop 1
	v_mov_b32_dpp v85, v85 row_half_mirror row_mask:0xf bank_mask:0xf
	v_pk_mul_f32 v[106:107], v[60:61], v[112:113]
	v_mul_f32_e32 v90, v0, v123
	v_add_f32_e32 v105, v107, v106
	v_mul_f32_e32 v89, v90, v89
	s_waitcnt lgkmcnt(0)
	v_cndmask_b32_e64 v85, v85, -v85, s[40:41]
	v_pk_mul_f32 v[84:85], v[62:63], v[84:85]
	v_mul_f32_e32 v90, v1, v123
	v_add_f32_e32 v106, v85, v84
	s_nop 1
	v_mov_b32_dpp v84, v114 quad_perm:[3,2,1,0] row_mask:0xf bank_mask:0xf
	s_nop 1
	v_mov_b32_dpp v84, v84 row_half_mirror row_mask:0xf bank_mask:0xf
	v_mul_f32_e32 v90, v90, v102
	v_mul_f32_e32 v102, v21, v123
	v_mul_f32_e32 v102, v102, v119
	v_mul_f32_e32 v93, v3, v123
	s_waitcnt lgkmcnt(0)
; __device__ __forceinline__ void phase_prep(KA a, int l, int vcu, int G, int wave) {
;     ...
;         for (int which = 0; which < 2; ++which) {
;             float v[24];
;             unpack8(which ? k0 : q0, v); unpack8(which ? k1 : q1, v + 8); unpack8(which ? k2 : q2, v + 16);
;             float ss = 0.f;
; #pragma unroll
;             for (int e = 0; e < 24; ++e) ss += v[e] * v[e];
;             ss += __shfl_xor(ss, 1); ss += __shfl_xor(ss, 2); ss += __shfl_xor(ss, 4);
;             const float rs = rsqrtf(ss * (1.0f / QKD) + EPS) * (which ? 1.0f : 1.0f);
; #pragma unroll
;             for (int e = 0; e < 24; ++e) v[e] *= rs * (which ? gkv[e] : gqv[e]);
;             float o2[8];
; #pragma unroll
;             for (int e = 0; e < 8; ++e) { const float p = __shfl_xor(v[16 + e], 4); o2[e] = v[16 + e] * cc[e] + (j < 4 ? -p : p) * sn[e]; }
;             bf16* d = (bf16*)(a->ws + (which ? WS_K : WS_Q)) + ((size_t)hh * TP + t) * QKD + 8 * j;
;             *(u32x4*)d = pack8(v); *(u32x4*)(d + 64) = pack8(v + 8); *(u32x4*)(d + 128) = pack8(o2);
	v_cndmask_b32_e64 v115, v84, -v84, s[40:41]
	v_pk_mul_f32 v[84:85], v[56:57], v[114:115]
	v_mul_f32_e32 v93, v93, v104
	v_add_f32_e32 v107, v85, v84
	s_nop 1
	v_mov_b32_dpp v84, v116 quad_perm:[3,2,1,0] row_mask:0xf bank_mask:0xf
	s_nop 1
	v_mov_b32_dpp v84, v84 row_half_mirror row_mask:0xf bank_mask:0xf
	v_mul_f32_e32 v104, v23, v123
	v_mul_f32_e32 v104, v104, v121
	v_cvt_pk_bf16_f32 v114, v89, v90
	v_cvt_pk_bf16_f32 v115, v91, v93
	s_waitcnt lgkmcnt(0)
	v_cndmask_b32_e64 v117, v84, -v84, s[40:41]
	v_pk_mul_f32 v[84:85], v[58:59], v[116:117]
	v_cvt_pk_bf16_f32 v116, v94, v97
	v_cvt_pk_bf16_f32 v117, v98, v101
	v_lshlrev_b32_e32 v89, 16, v72
	v_add_f32_e32 v108, v85, v84
	s_nop 1
	v_mov_b32_dpp v84, v118 quad_perm:[3,2,1,0] row_mask:0xf bank_mask:0xf
	s_nop 1
	v_mov_b32_dpp v84, v84 row_half_mirror row_mask:0xf bank_mask:0xf
	v_lshlrev_b32_e32 v94, 16, v75
	v_and_b32_e32 v75, 0xffff0000, v75
	v_lshlrev_b32_e32 v97, 16, v69
	v_and_b32_e32 v98, 0xffff0000, v69
	s_waitcnt lgkmcnt(0)
	v_cndmask_b32_e64 v119, v84, -v84, s[40:41]
	v_pk_mul_f32 v[84:85], v[52:53], v[118:119]
	v_lshlrev_b32_e32 v101, 16, v71
	v_add_f32_e32 v109, v85, v84
	s_nop 1
	v_mov_b32_dpp v84, v120 quad_perm:[3,2,1,0] row_mask:0xf bank_mask:0xf
	s_nop 1
	v_mov_b32_dpp v84, v84 row_half_mirror row_mask:0xf bank_mask:0xf
	v_lshlrev_b32_e32 v69, 16, v64
	s_waitcnt lgkmcnt(0)
	v_cndmask_b32_e64 v121, v84, -v84, s[40:41]
	v_pk_mul_f32 v[84:85], v[54:55], v[120:121]
	s_nop 0
	v_add_f32_e32 v110, v85, v84
	s_nop 1
	v_mov_b32_dpp v84, v122 quad_perm:[3,2,1,0] row_mask:0xf bank_mask:0xf
	s_nop 1
	v_mov_b32_dpp v84, v84 row_half_mirror row_mask:0xf bank_mask:0xf
	s_waitcnt lgkmcnt(0)
	v_cndmask_b32_e64 v123, v84, -v84, s[40:41]
	v_pk_mul_f32 v[84:85], v[48:49], v[122:123]
	s_nop 0
	v_add_f32_e32 v111, v85, v84
	s_nop 1
	v_mov_b32_dpp v84, v124 quad_perm:[3,2,1,0] row_mask:0xf bank_mask:0xf
	s_nop 1
	v_mov_b32_dpp v84, v84 row_half_mirror row_mask:0xf bank_mask:0xf
	s_waitcnt lgkmcnt(0)
	v_cndmask_b32_e64 v125, v84, -v84, s[40:41]
	v_pk_mul_f32 v[84:85], v[50:51], v[124:125]
	s_nop 0
	v_add_f32_e32 v112, v85, v84
	v_lshl_add_u64 v[84:85], v[82:83], 0, v[148:149]
	v_add_co_u32_e32 v118, vcc, s3, v84
	s_mov_b32 s3, 0x298d0000
	s_nop 0
	v_addc_co_u32_e32 v119, vcc, 0, v85, vcc
	global_store_dwordx4 v[118:119], v[114:117], off
	v_cvt_pk_bf16_f32 v90, v92, v95
	v_cvt_pk_bf16_f32 v91, v96, v99
	v_cvt_pk_bf16_f32 v92, v100, v102
	v_cvt_pk_bf16_f32 v93, v103, v104
	global_store_dwordx4 v[118:119], v[90:93], off offset:128
	v_lshlrev_b32_e32 v95, 16, v68
	v_and_b32_e32 v96, 0xffff0000, v68
	v_cvt_pk_bf16_f32 v90, v105, v106
	v_cvt_pk_bf16_f32 v91, v107, v108
	v_cvt_pk_bf16_f32 v92, v109, v110
	v_cvt_pk_bf16_f32 v93, v111, v112
	global_store_dwordx4 v[118:119], v[90:93], off offset:256
	v_lshlrev_b32_e32 v99, 16, v70
	v_and_b32_e32 v100, 0xffff0000, v70
	v_and_b32_e32 v90, 0xffff0000, v72
	v_mul_f32_e32 v72, v90, v90
	v_lshlrev_b32_e32 v91, 16, v73
	v_fmac_f32_e32 v72, v89, v89
	v_and_b32_e32 v92, 0xffff0000, v73
	v_fmac_f32_e32 v72, v91, v91
	v_lshlrev_b32_e32 v93, 16, v74
	v_fmac_f32_e32 v72, v92, v92
	v_and_b32_e32 v74, 0xffff0000, v74
	v_fmac_f32_e32 v72, v93, v93
	v_fmac_f32_e32 v72, v74, v74
	v_fmac_f32_e32 v72, v94, v94
	v_fmac_f32_e32 v72, v75, v75
	v_fmac_f32_e32 v72, v95, v95
	v_fmac_f32_e32 v72, v96, v96
	v_fmac_f32_e32 v72, v97, v97
	v_fmac_f32_e32 v72, v98, v98
	v_fmac_f32_e32 v72, v99, v99
	v_fmac_f32_e32 v72, v100, v100
	v_and_b32_e32 v102, 0xffff0000, v71
	v_fmac_f32_e32 v72, v101, v101
	v_and_b32_e32 v68, 0xffff0000, v64
	v_fmac_f32_e32 v72, v102, v102
	v_pk_mul_f32 v[70:71], v[68:69], v[68:69]
	v_lshl_add_u64 v[82:83], v[82:83], 0, s[54:55]
	v_add_f32_e32 v64, v71, v72
	v_add_f32_e32 v72, v70, v64
	v_and_b32_e32 v64, 0xffff0000, v65
	v_lshlrev_b32_e32 v65, 16, v65
	v_pk_mul_f32 v[70:71], v[64:65], v[64:65]
	s_nop 0
	v_add_f32_e32 v71, v71, v72
	v_add_f32_e32 v103, v70, v71
	v_and_b32_e32 v70, 0xffff0000, v66
	v_lshlrev_b32_e32 v71, 16, v66
	v_pk_mul_f32 v[72:73], v[70:71], v[70:71]
	s_nop 0
	v_add_f32_e32 v66, v73, v103
	v_add_f32_e32 v103, v72, v66
	v_and_b32_e32 v66, 0xffff0000, v67
	v_lshlrev_b32_e32 v67, 16, v67
	v_pk_mul_f32 v[72:73], v[66:67], v[66:67]
	s_nop 0
	v_add_f32_e32 v73, v73, v103
	v_add_f32_e32 v72, v72, v73
	s_nop 1
	v_add_f32_dpp v72, v72, v72 quad_perm:[1,0,3,2] row_mask:0xf bank_mask:0xf
	s_nop 1
	v_add_f32_dpp v72, v72, v72 quad_perm:[2,3,0,1] row_mask:0xf bank_mask:0xf
	s_nop 1
	v_add_f32_dpp v72, v72, v72 row_half_mirror row_mask:0xf bank_mask:0xf
	v_fmamk_f32 v72, v72, 0x3baaaaab, v154
	v_cmp_gt_f32_e32 vcc, s9, v72
	v_mul_f32_e32 v73, 0x4b800000, v72
	s_nop 0
	v_cndmask_b32_e32 v72, v72, v73, vcc
	v_rsq_f32_e32 v72, v72
	s_nop 0
	v_mul_f32_e32 v73, 0x45800000, v72
	v_cndmask_b32_e32 v73, v72, v73, vcc
	v_mul_f32_e32 v72, v8, v73
	v_mul_f32_e32 v89, v72, v89
	v_mul_f32_e32 v72, v9, v73
	v_mul_f32_e32 v103, v72, v90
	v_mul_f32_e32 v72, v10, v73
	v_mul_f32_e32 v104, v72, v91
	v_mul_f32_e32 v72, v11, v73
	v_mul_f32_e32 v105, v72, v92
	v_mul_f32_e32 v72, v12, v73
	v_mul_f32_e32 v106, v72, v93
	v_mul_f32_e32 v72, v13, v73
	v_mul_f32_e32 v107, v72, v74
	v_mul_f32_e32 v72, v14, v73
	v_mul_f32_e32 v94, v72, v94
	v_mul_f32_e32 v72, v15, v73
	v_mul_f32_e32 v108, v72, v75
	v_mul_f32_e32 v72, v24, v73
	v_mul_f32_e32 v95, v72, v95
	v_mul_f32_e32 v72, v25, v73
	v_mul_f32_e32 v96, v72, v96
	v_mul_f32_e32 v72, v26, v73
	v_mul_f32_e32 v97, v72, v97
	v_mul_f32_e32 v72, v27, v73
	v_mul_f32_e32 v98, v72, v98
	v_mul_f32_e32 v72, v28, v73
	v_mul_f32_e32 v99, v72, v99
	v_mul_f32_e32 v72, v29, v73
	v_mul_f32_e32 v100, v72, v100
	v_mul_f32_e32 v72, v30, v73
	v_mul_f32_e32 v101, v72, v101
	v_mul_f32_e32 v72, v31, v73
	v_mul_f32_e32 v102, v72, v102
	v_mul_f32_e32 v72, v32, v73
	v_mul_f32_e32 v72, v72, v69
	v_mul_f32_e32 v69, v33, v73
	v_mul_f32_e32 v68, v69, v68
	v_mul_f32_e32 v69, v34, v73
	v_mul_f32_e32 v74, v69, v65
	v_mul_f32_e32 v65, v35, v73
	v_mul_f32_e32 v64, v65, v64
	v_mul_f32_e32 v65, v36, v73
	v_mul_f32_e32 v90, v65, v71
	v_mul_f32_e32 v65, v37, v73
	v_mul_f32_e32 v70, v65, v70
	v_mul_f32_e32 v65, v38, v73
	v_mul_f32_e32 v92, v65, v67
	v_mul_f32_e32 v65, v39, v73
	v_mul_f32_e32 v66, v65, v66
	s_nop 1
	v_mov_b32_dpp v65, v72 quad_perm:[3,2,1,0] row_mask:0xf bank_mask:0xf
	s_nop 1
	v_mov_b32_dpp v65, v65 row_half_mirror row_mask:0xf bank_mask:0xf
	s_waitcnt lgkmcnt(0)
; __device__ __forceinline__ void phase_prep(KA a, int l, int vcu, int G, int wave) {
;     ...
;             for (int e = 0; e < 24; ++e) v[e] *= rs * (which ? gkv[e] : gqv[e]);
;             float o2[8];
; #pragma unroll
;             for (int e = 0; e < 8; ++e) { const float p = __shfl_xor(v[16 + e], 4); o2[e] = v[16 + e] * cc[e] + (j < 4 ? -p : p) * sn[e]; }
;             bf16* d = (bf16*)(a->ws + (which ? WS_K : WS_Q)) + ((size_t)hh * TP + t) * QKD + 8 * j;
;             *(u32x4*)d = pack8(v); *(u32x4*)(d + 64) = pack8(v + 8); *(u32x4*)(d + 128) = pack8(o2);
;         }
	v_cndmask_b32_e64 v73, v65, -v65, s[40:41]
	v_pk_mul_f32 v[60:61], v[60:61], v[72:73]
	s_nop 0
	v_add_f32_e32 v72, v61, v60
	s_nop 1
	v_mov_b32_dpp v60, v68 quad_perm:[3,2,1,0] row_mask:0xf bank_mask:0xf
	s_nop 1
	v_mov_b32_dpp v60, v60 row_half_mirror row_mask:0xf bank_mask:0xf
	s_waitcnt lgkmcnt(0)
	v_cndmask_b32_e64 v69, v60, -v60, s[40:41]
	v_pk_mul_f32 v[60:61], v[62:63], v[68:69]
	s_nop 0
	v_add_f32_e32 v60, v61, v60
	s_nop 1
	v_mov_b32_dpp v61, v74 quad_perm:[3,2,1,0] row_mask:0xf bank_mask:0xf
	s_nop 1
	v_mov_b32_dpp v61, v61 row_half_mirror row_mask:0xf bank_mask:0xf
	s_waitcnt lgkmcnt(0)
	v_cndmask_b32_e64 v75, v61, -v61, s[40:41]
	v_pk_mul_f32 v[56:57], v[56:57], v[74:75]
	s_nop 0
	v_add_f32_e32 v61, v57, v56
	s_nop 1
	v_mov_b32_dpp v56, v64 quad_perm:[3,2,1,0] row_mask:0xf bank_mask:0xf
	s_nop 1
	v_mov_b32_dpp v56, v56 row_half_mirror row_mask:0xf bank_mask:0xf
	s_waitcnt lgkmcnt(0)
	v_cndmask_b32_e64 v65, v56, -v56, s[40:41]
	v_pk_mul_f32 v[56:57], v[58:59], v[64:65]
	s_nop 0
	v_add_f32_e32 v56, v57, v56
	s_nop 1
	v_mov_b32_dpp v57, v90 quad_perm:[3,2,1,0] row_mask:0xf bank_mask:0xf
	s_nop 1
	v_mov_b32_dpp v57, v57 row_half_mirror row_mask:0xf bank_mask:0xf
	s_waitcnt lgkmcnt(0)
	v_cndmask_b32_e64 v91, v57, -v57, s[40:41]
	v_pk_mul_f32 v[52:53], v[52:53], v[90:91]
	s_nop 0
	v_add_f32_e32 v57, v53, v52
	s_nop 1
	v_mov_b32_dpp v52, v70 quad_perm:[3,2,1,0] row_mask:0xf bank_mask:0xf
	s_nop 1
	v_mov_b32_dpp v52, v52 row_half_mirror row_mask:0xf bank_mask:0xf
	s_waitcnt lgkmcnt(0)
	v_cndmask_b32_e64 v71, v52, -v52, s[40:41]
	v_pk_mul_f32 v[52:53], v[54:55], v[70:71]
	s_nop 0
	v_add_f32_e32 v54, v53, v52
	s_nop 1
	v_mov_b32_dpp v52, v92 quad_perm:[3,2,1,0] row_mask:0xf bank_mask:0xf
	s_nop 1
	v_mov_b32_dpp v52, v52 row_half_mirror row_mask:0xf bank_mask:0xf
	s_waitcnt lgkmcnt(0)
	v_cndmask_b32_e64 v93, v52, -v52, s[40:41]
	v_pk_mul_f32 v[48:49], v[48:49], v[92:93]
	v_add_co_u32_e32 v52, vcc, s3, v84
	v_add_f32_e32 v55, v49, v48
	s_nop 1
	v_mov_b32_dpp v48, v66 quad_perm:[3,2,1,0] row_mask:0xf bank_mask:0xf
	s_nop 1
	v_mov_b32_dpp v48, v48 row_half_mirror row_mask:0xf bank_mask:0xf
	v_addc_co_u32_e32 v53, vcc, 0, v85, vcc
	s_waitcnt lgkmcnt(0)
	v_cndmask_b32_e64 v67, v48, -v48, s[40:41]
	v_pk_mul_f32 v[48:49], v[50:51], v[66:67]
	s_nop 0
	v_add_f32_e32 v58, v49, v48
	v_cvt_pk_bf16_f32 v48, v89, v103
	v_cvt_pk_bf16_f32 v49, v104, v105
	v_cvt_pk_bf16_f32 v50, v106, v107
	v_cvt_pk_bf16_f32 v51, v94, v108
	global_store_dwordx4 v[52:53], v[48:51], off
	s_nop 1
	v_cvt_pk_bf16_f32 v48, v95, v96
	v_cvt_pk_bf16_f32 v49, v97, v98
	v_cvt_pk_bf16_f32 v50, v99, v100
	v_cvt_pk_bf16_f32 v51, v101, v102
	global_store_dwordx4 v[52:53], v[48:51], off offset:128
	s_nop 1
	v_cvt_pk_bf16_f32 v48, v72, v60
	v_cvt_pk_bf16_f32 v49, v61, v56
	v_cvt_pk_bf16_f32 v50, v57, v54
	v_cvt_pk_bf16_f32 v51, v55, v58
	global_store_dwordx4 v[52:53], v[48:51], off offset:256
	s_cbranch_scc0 .LBB0_375

; __device__ __forceinline__ unsigned pk2(float lo, float hi) { return pg8::cvt_pk_bf16(lo, hi); }
; __device__ __forceinline__ float bflo(unsigned w) { return __uint_as_float(w << 16); }
; __device__ __forceinline__ float bfhi(unsigned w) { return __uint_as_float(w & 0xffff0000u); }
; __device__ __forceinline__ void phase_lat(KA a, int l, int vcu, int G, int wave) {
;     ...
;     for (int t = gw; t < T_; t += NGW) {
;         const bf16* row = (const bf16*)(a->ws + WS_ATT) + (size_t)t * 1024;
;         const u32x4 q = *(const u32x4*)(row + lane * 8); const u32x2 k = *(const u32x2*)(row + 512 + lane * 4);
;         float qv[8] = {bflo(q.x), bfhi(q.x), bflo(q.y), bfhi(q.y), bflo(q.z), bfhi(q.z), bflo(q.w), bfhi(q.w)};
;         float kv[4] = {bflo(k.x), bfhi(k.x), bflo(k.y), bfhi(k.y)};
;         float sq = 0.f, sk = 0.f;
; #pragma unroll
;         for (int e = 0; e < 8; ++e) sq += qv[e] * qv[e];
; #pragma unroll
;         for (int e = 0; e < 4; ++e) sk += kv[e] * kv[e];
;         sq = wave_sum(sq); sk = wave_sum(sk);
;         const float rq = rsqrtf(sq * (1.0f / QL) + EPS), rk = rsqrtf(sk * (1.0f / KVL) + EPS);
;         const f32x4 g0 = *(const f32x4*)(gq + lane * 8), g1 = *(const f32x4*)(gq + lane * 8 + 4), g2 = *(const f32x4*)(gk + lane * 4);
;         u32x4 wq; wq.x = pk2(qv[0] * rq * g0.x, qv[1] * rq * g0.y); wq.y = pk2(qv[2] * rq * g0.z, qv[3] * rq * g0.w);
;         wq.z = pk2(qv[4] * rq * g1.x, qv[5] * rq * g1.y); wq.w = pk2(qv[6] * rq * g1.z, qv[7] * rq * g1.w);
;         *(u32x4*)((bf16*)(a->ws + WS_CQN) + (size_t)t * QL + lane * 8) = wq;
;         u32x2 wk; wk.x = pk2(kv[0] * rk * g2.x, kv[1] * rk * g2.y); wk.y = pk2(kv[2] * rk * g2.z, kv[3] * rk * g2.w);
;         *(u32x2*)((bf16*)(a->ws + WS_CKVN) + (size_t)t * KVL + lane * 4) = wk;
;     }
.LBB0_429:
	v_lshl_add_u64 v[12:13], s[54:55], 0, v[10:11]
	global_load_dwordx4 v[32:35], v[12:13], off
	v_lshl_add_u64 v[12:13], s[54:55], 0, v[8:9]
	global_load_dwordx2 v[12:13], v[12:13], off
	s_add_i32 s42, s42, s44
	s_add_u32 s54, s54, s52
	s_addc_u32 s55, s55, s53
	s_cmpk_gt_i32 s42, 0x200f
	s_waitcnt vmcnt(1)
	v_lshlrev_b32_e32 v24, 16, v32
	v_and_b32_e32 v25, 0xffff0000, v32
	v_and_b32_e32 v20, 0xffff0000, v33
	v_lshlrev_b32_e32 v21, 16, v33
	v_and_b32_e32 v17, s0, v35
	v_and_b32_e32 v16, 0xffff0000, v34
	v_pk_mul_f32 v[32:33], v[24:25], v[24:25]
	v_pk_mul_f32 v[36:37], v[20:21], v[20:21]
	v_pk_mul_f32 v[38:39], v[16:17], v[16:17]
	v_add_f32_e32 v17, v32, v33
	v_add_f32_e32 v17, v37, v17
	v_lshlrev_b32_e32 v23, 16, v34
	v_mov_b32_e32 v22, v16
	s_waitcnt vmcnt(0)
	v_lshlrev_b32_e32 v14, 16, v12
	v_and_b32_e32 v15, 0xffff0000, v12
	v_add_f32_e32 v32, v36, v17
	v_and_b32_e32 v18, 0xffff0000, v35
	v_lshlrev_b32_e32 v19, 16, v35
	v_pk_mul_f32 v[40:41], v[14:15], v[14:15]
	v_and_b32_e32 v12, 0xffff0000, v13
	v_lshlrev_b32_e32 v13, 16, v13
	v_pk_fma_f32 v[32:33], v[22:23], v[22:23], v[32:33] op_sel_hi:[1,1,0]
	v_pk_mul_f32 v[34:35], v[18:19], v[18:19]
	v_pk_mul_f32 v[42:43], v[12:13], v[12:13]
	v_mov_b32_e32 v36, v40
	v_mov_b32_e32 v37, v38
	v_mov_b32_e32 v32, v41
	v_pk_add_f32 v[32:33], v[36:37], v[32:33]
	v_mov_b32_e32 v36, v43
	v_mov_b32_e32 v37, v35
	v_pk_add_f32 v[32:33], v[36:37], v[32:33]
	v_mov_b32_e32 v43, v34
	v_pk_add_f32 v[32:33], v[42:43], v[32:33]
	s_nop 1
	v_add_f32_dpp v32, v32, v32 quad_perm:[1,0,3,2] row_mask:0xf bank_mask:0xf
	v_add_f32_dpp v33, v33, v33 quad_perm:[1,0,3,2] row_mask:0xf bank_mask:0xf
	s_nop 0
	s_nop 1
	v_add_f32_dpp v32, v32, v32 quad_perm:[2,3,0,1] row_mask:0xf bank_mask:0xf
	v_add_f32_dpp v33, v33, v33 quad_perm:[2,3,0,1] row_mask:0xf bank_mask:0xf
	s_nop 0
	s_nop 1
	v_add_f32_dpp v32, v32, v32 row_half_mirror row_mask:0xf bank_mask:0xf
	v_add_f32_dpp v33, v33, v33 row_half_mirror row_mask:0xf bank_mask:0xf
	s_nop 0
	s_nop 1
	v_add_f32_dpp v32, v32, v32 row_mirror row_mask:0xf bank_mask:0xf
	v_add_f32_dpp v33, v33, v33 row_mirror row_mask:0xf bank_mask:0xf
	s_nop 0
	ds_bpermute_b32 v35, v30, v33
	ds_bpermute_b32 v34, v30, v32
	s_waitcnt lgkmcnt(0)
	v_pk_add_f32 v[32:33], v[32:33], v[34:35]
	ds_bpermute_b32 v35, v31, v33
	ds_bpermute_b32 v34, v31, v32
	s_waitcnt lgkmcnt(0)
	v_pk_add_f32 v[32:33], v[32:33], v[34:35]
	s_nop 0
	v_pk_fma_f32 v[32:33], v[32:33], s[0:1], v[154:155] op_sel_hi:[1,1,0]
	s_nop 0
	v_mul_f32_e32 v17, 0x4b800000, v33
	v_cmp_gt_f32_e64 s[40:41], s3, v33
	v_cmp_gt_f32_e32 vcc, s3, v32
	s_nop 0
	v_cndmask_b32_e64 v17, v33, v17, s[40:41]
	v_rsq_f32_e32 v17, v17
	s_nop 0
	v_mul_f32_e32 v22, 0x45800000, v17
	v_cndmask_b32_e64 v17, v17, v22, s[40:41]
	v_mul_f32_e32 v22, 0x4b800000, v32
	v_cndmask_b32_e32 v22, v32, v22, vcc
	v_rsq_f32_e32 v22, v22
	v_mul_f32_e32 v20, v17, v20
	v_mul_f32_e32 v24, v17, v24
	v_mul_f32_e32 v25, v17, v25
	v_mul_f32_e32 v32, 0x45800000, v22
	v_cndmask_b32_e32 v22, v22, v32, vcc
	v_mul_f32_e32 v21, v17, v21
	v_mul_f32_e32 v16, v17, v16
	v_mul_f32_e32 v14, v22, v14
	v_mul_f32_e32 v15, v22, v15
	v_mul_f32_e32 v13, v22, v13
	v_mul_f32_e32 v12, v22, v12
	v_mul_f32_e32 v16, v65, v16
	v_mul_f32_e32 v20, v71, v20
	v_mul_f32_e32 v24, v68, v24
	v_mul_f32_e32 v25, v69, v25
	v_cvt_pk_bf16_f32 v36, v24, v25
	v_mul_f32_e32 v21, v70, v21
	v_cvt_pk_bf16_f32 v37, v21, v20
	v_mul_f32_e32 v20, v17, v23
	v_mul_f32_e32 v20, v64, v20
	v_cvt_pk_bf16_f32 v38, v20, v16
	v_mul_f32_e32 v16, v17, v19
	v_mul_f32_e32 v17, v17, v18
	v_mul_f32_e32 v14, v72, v14
	v_mul_f32_e32 v15, v73, v15
	v_mul_f32_e32 v16, v66, v16
	v_mul_f32_e32 v17, v67, v17
	v_cvt_pk_bf16_f32 v39, v16, v17
	global_store_dwordx4 v[6:7], v[36:39], off
	s_nop 1
	v_cvt_pk_bf16_f32 v14, v14, v15
	v_mul_f32_e32 v13, v74, v13
	v_mul_f32_e32 v12, v75, v12
	v_cvt_pk_bf16_f32 v15, v13, v12
	global_store_dwordx2 v[4:5], v[14:15], off
	v_lshl_add_u64 v[4:5], v[4:5], 0, s[46:47]
	v_lshl_add_u64 v[6:7], v[6:7], 0, s[48:49]
	s_cbranch_scc0 .LBB0_429

; __device__ __forceinline__ unsigned pk2(float lo, float hi) { return pg8::cvt_pk_bf16(lo, hi); }
; __device__ __forceinline__ void norm_row(const float* src, const float* g, bf16* dst, float* hdst, int lane) {
;     f32x4 v[8]; float ss = 0.f;
; #pragma unroll
;     for (int j = 0; j < 8; ++j) { v[j] = src ? *(const f32x4*)(src + 4 * lane + 256 * j) : (f32x4){0.f, 0.f, 0.f, 0.f}; ss += v[j].x * v[j].x + v[j].y * v[j].y + v[j].z * v[j].z + v[j].w * v[j].w; }
;     ss = wave_sum(ss);
;     const float rstd = rsqrtf(ss * (1.0f / DM) + EPS);
; #pragma unroll
;     for (int j = 0; j < 8; ++j) {
;         const f32x4 gg = *(const f32x4*)(g + 4 * lane + 256 * j);
;         u32x2 w; w.x = pk2(v[j].x * rstd * gg.x, v[j].y * rstd * gg.y); w.y = pk2(v[j].z * rstd * gg.z, v[j].w * rstd * gg.w);
;         *(u32x2*)(dst + 4 * lane + 256 * j) = w;
;         if (hdst) *(f32x4*)(hdst + 4 * lane + 256 * j) = v[j];
;     }
; }
.LBB0_437:
	v_lshl_add_u64 v[0:1], s[16:17], 0, v[44:45]
	v_add_co_u32_e32 v2, vcc, 0x17600000, v0
	v_lshl_add_u64 v[60:61], s[16:17], 0, v[42:43]
	s_nop 0
	v_addc_co_u32_e32 v3, vcc, 0, v1, vcc
	global_load_dwordx4 v[28:31], v[2:3], off
	global_load_dwordx4 v[24:27], v[2:3], off offset:1024
	global_load_dwordx4 v[20:23], v[2:3], off offset:2048
	global_load_dwordx4 v[16:19], v[2:3], off offset:3072
	v_add_co_u32_e32 v0, vcc, s26, v0
	s_add_i32 s20, s20, s40
	s_nop 0
	v_addc_co_u32_e32 v1, vcc, 0, v1, vcc
	global_load_dwordx4 v[12:15], v[0:1], off
	global_load_dwordx4 v[8:11], v[0:1], off offset:1024
	global_load_dwordx4 v[96:99], v[0:1], off offset:2048
	global_load_dwordx4 v[100:103], v[0:1], off offset:3072
	v_lshl_add_u64 v[42:43], v[42:43], 0, s[42:43]
	v_lshl_add_u64 v[44:45], v[44:45], 0, s[44:45]
	s_cmpk_gt_i32 s20, 0x200f
	s_waitcnt vmcnt(0)
	v_mul_f32_e32 v4, v29, v29
	v_mul_f32_e32 v5, v25, v25
	v_fmac_f32_e32 v4, v28, v28
	v_fmac_f32_e32 v5, v24, v24
	v_fmac_f32_e32 v4, v30, v30
	v_fmac_f32_e32 v5, v26, v26
	v_fmac_f32_e32 v4, v31, v31
	v_fmac_f32_e32 v5, v27, v27
	v_add_f32_e32 v4, v4, v5
	v_mul_f32_e32 v5, v21, v21
	v_fmac_f32_e32 v5, v20, v20
	v_mul_f32_e32 v2, v17, v17
	v_fmac_f32_e32 v5, v22, v22
	v_fmac_f32_e32 v2, v16, v16
	v_fmac_f32_e32 v5, v23, v23
	v_fmac_f32_e32 v2, v18, v18
	v_add_f32_e32 v4, v4, v5
	v_fmac_f32_e32 v2, v19, v19
	v_add_f32_e32 v6, v4, v2
	v_mov_b32_e32 v4, v13
	v_mov_b32_e32 v5, v9
	v_mov_b32_e32 v2, v12
	v_mov_b32_e32 v3, v8
	v_pk_mul_f32 v[4:5], v[4:5], v[4:5]
	s_nop 0
	v_pk_fma_f32 v[2:3], v[2:3], v[2:3], v[4:5]
	v_mov_b32_e32 v4, v14
	v_mov_b32_e32 v5, v10
	v_pk_fma_f32 v[2:3], v[4:5], v[4:5], v[2:3]
	v_mov_b32_e32 v4, v15
	v_mov_b32_e32 v5, v11
	v_pk_fma_f32 v[2:3], v[4:5], v[4:5], v[2:3]
	s_nop 0
	v_add_f32_e32 v2, v6, v2
	v_add_f32_e32 v56, v2, v3
	v_mov_b32_e32 v4, v96
	v_mov_b32_e32 v5, v97
	v_mov_b32_e32 v6, v98
	v_mov_b32_e32 v7, v99
	s_nop 0
	v_mov_b32_e32 v0, v100
	v_mov_b32_e32 v1, v101
	v_mov_b32_e32 v2, v102
	v_mov_b32_e32 v3, v103
	v_mov_b32_e32 v54, v5
	v_mov_b32_e32 v55, v1
	v_mov_b32_e32 v46, v4
	v_mov_b32_e32 v47, v0
	v_pk_mul_f32 v[54:55], v[54:55], v[54:55]
	s_nop 0
	v_pk_fma_f32 v[46:47], v[46:47], v[46:47], v[54:55]
	v_mov_b32_e32 v54, v6
	v_mov_b32_e32 v55, v2
	v_pk_fma_f32 v[46:47], v[54:55], v[54:55], v[46:47]
	v_mov_b32_e32 v54, v7
	v_mov_b32_e32 v55, v3
	v_pk_fma_f32 v[46:47], v[54:55], v[54:55], v[46:47]
	s_nop 0
	v_add_f32_e32 v46, v56, v46
	v_add_f32_e32 v46, v46, v47
	s_nop 1
	s_waitcnt lgkmcnt(0)
	v_add_f32_dpp v46, v46, v46 quad_perm:[1,0,3,2] row_mask:0xf bank_mask:0xf
	s_nop 1
	s_waitcnt lgkmcnt(0)
	v_add_f32_dpp v46, v46, v46 quad_perm:[2,3,0,1] row_mask:0xf bank_mask:0xf
	s_nop 1
	s_waitcnt lgkmcnt(0)
	v_add_f32_dpp v46, v46, v46 row_half_mirror row_mask:0xf bank_mask:0xf
	s_nop 1
	s_waitcnt lgkmcnt(0)
	v_add_f32_dpp v46, v46, v46 row_mirror row_mask:0xf bank_mask:0xf
	ds_bpermute_b32 v47, v52, v46
	s_waitcnt lgkmcnt(0)
	v_add_f32_e32 v46, v46, v47
	ds_bpermute_b32 v47, v53, v46
	s_waitcnt lgkmcnt(0)
	v_add_f32_e32 v46, v46, v47
	v_fmamk_f32 v46, v46, 0x3a000000, v154
	v_cmp_gt_f32_e32 vcc, s54, v46
	v_mul_f32_e32 v47, 0x4b800000, v46
	s_nop 0
	v_cndmask_b32_e32 v46, v46, v47, vcc
	v_rsq_f32_e32 v46, v46
	s_nop 0
	v_mul_f32_e32 v47, 0x45800000, v46
	v_cndmask_b32_e32 v54, v46, v47, vcc
	v_mul_f32_e32 v28, v28, v54
	v_mul_f32_e32 v29, v29, v54
	v_mul_f32_e32 v24, v24, v54
	v_mul_f32_e32 v25, v25, v54
	v_mul_f32_e32 v20, v20, v54
	v_mul_f32_e32 v21, v21, v54
	v_mul_f32_e32 v16, v16, v54
	v_mul_f32_e32 v17, v17, v54
	v_mul_f32_e32 v12, v12, v54
	v_mul_f32_e32 v13, v13, v54
	v_mul_f32_e32 v8, v8, v54
	v_mul_f32_e32 v9, v9, v54
	v_mul_f32_e32 v4, v4, v54
	v_mul_f32_e32 v5, v5, v54
	v_mul_f32_e32 v0, v0, v54
	v_mul_f32_e32 v1, v1, v54
	v_mul_f32_e32 v28, v64, v28
	v_mul_f32_e32 v29, v65, v29
	v_cvt_pk_bf16_f32 v46, v28, v29
	v_mul_f32_e32 v28, v30, v54
	v_mul_f32_e32 v28, v66, v28
	v_mul_f32_e32 v29, v31, v54
	v_mul_f32_e32 v29, v67, v29
	v_cvt_pk_bf16_f32 v47, v28, v29
	v_add_co_u32_e32 v28, vcc, s0, v60
	s_nop 1
	v_addc_co_u32_e32 v29, vcc, 0, v61, vcc
	global_store_dwordx2 v[28:29], v[46:47], off
	v_mul_f32_e32 v24, v68, v24
	v_mul_f32_e32 v25, v69, v25
	v_cvt_pk_bf16_f32 v24, v24, v25
	v_mul_f32_e32 v25, v26, v54
	v_mul_f32_e32 v25, v70, v25
	v_mul_f32_e32 v26, v27, v54
	v_mul_f32_e32 v26, v71, v26
	v_cvt_pk_bf16_f32 v25, v25, v26
	global_store_dwordx2 v[28:29], v[24:25], off offset:512
	v_mul_f32_e32 v20, v72, v20
	v_mul_f32_e32 v21, v73, v21
	v_cvt_pk_bf16_f32 v20, v20, v21
	v_mul_f32_e32 v21, v22, v54
	v_mul_f32_e32 v21, v74, v21
	v_mul_f32_e32 v22, v23, v54
	v_mul_f32_e32 v22, v75, v22
	v_cvt_pk_bf16_f32 v21, v21, v22
	global_store_dwordx2 v[28:29], v[20:21], off offset:1024
	v_mul_f32_e32 v16, v16, v76
	v_mul_f32_e32 v17, v17, v77
	v_cvt_pk_bf16_f32 v16, v16, v17
	v_mul_f32_e32 v17, v18, v54
	v_mul_f32_e32 v17, v17, v78
	v_mul_f32_e32 v18, v19, v54
	v_mul_f32_e32 v18, v18, v79
	v_cvt_pk_bf16_f32 v17, v17, v18
	global_store_dwordx2 v[28:29], v[16:17], off offset:1536
	v_mul_f32_e32 v12, v12, v80
	v_mul_f32_e32 v13, v13, v81
	v_cvt_pk_bf16_f32 v12, v12, v13
	v_mul_f32_e32 v13, v14, v54
	v_mul_f32_e32 v13, v13, v82
	v_mul_f32_e32 v14, v15, v54
	v_mul_f32_e32 v14, v14, v83
	v_cvt_pk_bf16_f32 v13, v13, v14
	global_store_dwordx2 v[28:29], v[12:13], off offset:2048
	v_mul_f32_e32 v8, v8, v84
	v_mul_f32_e32 v9, v9, v85
	v_cvt_pk_bf16_f32 v8, v8, v9
	v_mul_f32_e32 v9, v10, v54
	v_mul_f32_e32 v9, v9, v86
	v_mul_f32_e32 v10, v11, v54
	v_mul_f32_e32 v10, v10, v87
	v_cvt_pk_bf16_f32 v9, v9, v10
	global_store_dwordx2 v[28:29], v[8:9], off offset:2560
	v_mul_f32_e32 v4, v4, v88
	v_mul_f32_e32 v5, v5, v89
	v_cvt_pk_bf16_f32 v4, v4, v5
	v_mul_f32_e32 v5, v6, v54
	v_mul_f32_e32 v5, v5, v90
	v_mul_f32_e32 v6, v7, v54
	v_mul_f32_e32 v6, v6, v91
	v_cvt_pk_bf16_f32 v5, v5, v6
	global_store_dwordx2 v[28:29], v[4:5], off offset:3072
	v_mul_f32_e32 v0, v0, v92
	v_mul_f32_e32 v1, v1, v93
	v_cvt_pk_bf16_f32 v0, v0, v1
	v_mul_f32_e32 v1, v2, v54
	v_mul_f32_e32 v1, v1, v94
	v_mul_f32_e32 v2, v3, v54
	v_mul_f32_e32 v2, v2, v95
	v_cvt_pk_bf16_f32 v1, v1, v2
	global_store_dwordx2 v[28:29], v[0:1], off offset:3584
	s_cbranch_scc0 .LBB0_437
